# P8 SwiGLU epilogue: row scale folded into the sigmoid reciprocal (g*u*rcp((1+e)*x)), 8 packed scale multiplies per row group removed
# baseline (speedup 1.0000x reference)
; DI unsigned pk2(float lo, float hi) { const f32x2 v = {lo, hi}; const hwbf16x2 b = __builtin_convertvector(v, hwbf16x2); return __builtin_bit_cast(unsigned, b); }
; DI float frsq(float x) { return __builtin_amdgcn_rsqf(x); }
; DI float fsilu(float v) { return v * frcp(1.f + __expf(-v)); }
;     DI void operator()(const f32x4 (&acc)[2][2][4][2], const Unit& u, int wr, int wc, int fr, int fq) const {
;     ...
;                 if (mode == EPI_STORE || mode == EPI_Q) { if (rscale) rs = rscale[row]; }
;                 if (mode == EPI_SWIGLU) rs = frsq(rowsq[row] * (1.0f / DM) + 1e-6f);
; #pragma unroll
;                 for (int bj = 0; bj < 2; ++bj) {
;     ...
;                     } else {
;                         v0 = v0 * rs; v1 = v1 * rs;
;                         u32x2 w; w.x = pk2(fsilu(v0[0]) * v1[0], fsilu(v0[1]) * v1[1]); w.y = pk2(fsilu(v0[2]) * v1[2], fsilu(v0[3]) * v1[3]);
;                         *(u32x2*)(O + (size_t)row * ldc + (col >> 1)) = w;
.LBB0_1023:
	v_lshl_add_u32 v144, s22, 8, v152
	v_ashrrev_i32_e32 v145, 31, v144
	v_lshl_add_u64 v[148:149], v[144:145], 2, s[74:75]
	global_load_dword v236, v[148:149], off
	global_load_dword v237, v[148:149], off offset:64
	global_load_dword v238, v[148:149], off offset:128
	global_load_dword v239, v[148:149], off offset:192
	global_load_dword v240, v[148:149], off offset:512
	global_load_dword v241, v[148:149], off offset:576
	global_load_dword v242, v[148:149], off offset:640
	global_load_dword v243, v[148:149], off offset:704
	v_or_b32_e32 v162, 16, v144
	v_ashrrev_i32_e32 v163, 31, v162
	v_lshl_add_u64 v[170:171], v[162:163], 2, s[74:75]
	v_lshl_or_b32 v150, s40, 8, v154
	v_ashrrev_i32_e32 v150, 1, v150
	v_mov_b64_e32 v[146:147], s[44:45]
	v_ashrrev_i32_e32 v151, 31, v150
	v_mad_i64_i32 v[160:161], s[24:25], v144, s39, v[146:147]
	v_lshlrev_b64 v[150:151], 1, v[150:151]
	v_lshl_add_u64 v[160:161], v[160:161], 0, v[150:151]
	s_andn2_b64 vcc, exec, s[4:5]
	s_mov_b64 s[4:5], -1
	s_waitcnt vmcnt(7)
	v_fmamk_f32 v244, v236, 0x3a000000, v158
	v_rsq_f32_e32 v245, v244
	s_nop 0
	v_mul_f32_e32 v245, 0xbfb8aa3b, v245
	v_mul_f32_e32 v145, v245, v124
	v_mul_f32_e32 v159, v245, v125
	v_mul_f32_e32 v163, v245, v126
	v_mul_f32_e32 v164, v245, v127
	v_mul_f32_e32 v165, v245, v116
	v_mul_f32_e32 v166, v245, v117
	v_mul_f32_e32 v168, v245, v118
	v_mul_f32_e32 v172, v245, v119
	v_exp_f32_e32 v145, v145
	v_exp_f32_e32 v159, v159
	v_exp_f32_e32 v163, v163
	v_exp_f32_e32 v164, v164
	v_exp_f32_e32 v165, v165
	v_exp_f32_e32 v166, v166
	v_exp_f32_e32 v168, v168
	v_exp_f32_e32 v172, v172
	v_fma_f32 v145, v145, v244, v244
	v_fma_f32 v159, v159, v244, v244
	v_fma_f32 v163, v163, v244, v244
	v_fma_f32 v173, v164, v244, v244
	v_fma_f32 v174, v165, v244, v244
	v_fma_f32 v166, v166, v244, v244
	v_fma_f32 v168, v168, v244, v244
	v_fma_f32 v177, v172, v244, v244
	v_rcp_f32_e32 v164, v145
	v_rcp_f32_e32 v165, v159
	v_rcp_f32_e32 v172, v163
	v_rcp_f32_e32 v173, v173
	v_rcp_f32_e32 v174, v174
	v_rcp_f32_e32 v175, v166
	v_rcp_f32_e32 v176, v168
	v_rcp_f32_e32 v177, v177
	v_pk_mul_f32 v[124:125], v[124:125], v[164:165]
	v_pk_mul_f32 v[126:127], v[126:127], v[172:173]
	v_pk_mul_f32 v[116:117], v[116:117], v[174:175]
	v_pk_mul_f32 v[118:119], v[118:119], v[176:177]
	v_pk_mul_f32 v[120:121], v[120:121], v[124:125]
	v_pk_mul_f32 v[122:123], v[122:123], v[126:127]
	v_pk_mul_f32 v[112:113], v[112:113], v[116:117]
	v_pk_mul_f32 v[114:115], v[114:115], v[118:119]
	v_cvt_pk_bf16_f32 v116, v120, v121
	v_cvt_pk_bf16_f32 v117, v122, v123
	v_cvt_pk_bf16_f32 v112, v112, v113
	v_cvt_pk_bf16_f32 v113, v114, v115
	global_store_dwordx2 v[160:161], v[116:117], off
	global_store_dwordx2 v[160:161], v[112:113], off offset:128
	v_or_b32_e32 v112, 32, v144
	v_mad_i64_i32 v[114:115], s[24:25], v162, s39, v[146:147]
	v_lshl_add_u64 v[114:115], v[114:115], 0, v[150:151]
	s_waitcnt vmcnt(8)
	v_fmamk_f32 v244, v237, 0x3a000000, v158
	v_rsq_f32_e32 v245, v244
	v_ashrrev_i32_e32 v113, 31, v112
	v_lshl_add_u64 v[118:119], v[112:113], 2, s[74:75]
	v_mul_f32_e32 v245, 0xbfb8aa3b, v245
	v_mul_f32_e32 v113, v245, v108
	v_mul_f32_e32 v116, v245, v109
	v_mul_f32_e32 v117, v245, v110
	v_mul_f32_e32 v120, v245, v111
	v_mul_f32_e32 v121, v245, v100
	v_mul_f32_e32 v122, v245, v101
	v_mul_f32_e32 v123, v245, v102
	v_mul_f32_e32 v124, v245, v103
	v_exp_f32_e32 v113, v113
	v_exp_f32_e32 v116, v116
	v_exp_f32_e32 v117, v117
	v_exp_f32_e32 v120, v120
	v_exp_f32_e32 v121, v121
	v_exp_f32_e32 v122, v122
	v_exp_f32_e32 v123, v123
	v_exp_f32_e32 v124, v124
	v_fma_f32 v113, v113, v244, v244
	v_fma_f32 v125, v116, v244, v244
	v_fma_f32 v126, v117, v244, v244
	v_fma_f32 v127, v120, v244, v244
	v_fma_f32 v145, v121, v244, v244
	v_fma_f32 v159, v122, v244, v244
	v_fma_f32 v160, v123, v244, v244
	v_fma_f32 v161, v124, v244, v244
	v_rcp_f32_e32 v116, v113
	v_rcp_f32_e32 v117, v125
	v_rcp_f32_e32 v120, v126
	v_rcp_f32_e32 v121, v127
	v_rcp_f32_e32 v122, v145
	v_rcp_f32_e32 v123, v159
	v_rcp_f32_e32 v124, v160
	v_rcp_f32_e32 v125, v161
	v_pk_mul_f32 v[108:109], v[108:109], v[116:117]
	v_pk_mul_f32 v[110:111], v[110:111], v[120:121]
	v_pk_mul_f32 v[100:101], v[100:101], v[122:123]
	v_pk_mul_f32 v[102:103], v[102:103], v[124:125]
	v_pk_mul_f32 v[104:105], v[104:105], v[108:109]
	v_pk_mul_f32 v[106:107], v[106:107], v[110:111]
	v_pk_mul_f32 v[96:97], v[96:97], v[100:101]
	v_pk_mul_f32 v[98:99], v[98:99], v[102:103]
	v_cvt_pk_bf16_f32 v100, v104, v105
	v_cvt_pk_bf16_f32 v101, v106, v107
	v_cvt_pk_bf16_f32 v96, v96, v97
	v_cvt_pk_bf16_f32 v97, v98, v99
	global_store_dwordx2 v[114:115], v[100:101], off
	global_store_dwordx2 v[114:115], v[96:97], off offset:128
	v_or_b32_e32 v96, 48, v144
	v_mad_i64_i32 v[98:99], s[24:25], v112, s39, v[146:147]
	v_lshl_add_u64 v[98:99], v[98:99], 0, v[150:151]
	s_waitcnt vmcnt(9)
; DI unsigned pk2(float lo, float hi) { const f32x2 v = {lo, hi}; const hwbf16x2 b = __builtin_convertvector(v, hwbf16x2); return __builtin_bit_cast(unsigned, b); }
; DI float frsq(float x) { return __builtin_amdgcn_rsqf(x); }
; DI float fsilu(float v) { return v * frcp(1.f + __expf(-v)); }
;     DI void operator()(const f32x4 (&acc)[2][2][4][2], const Unit& u, int wr, int wc, int fr, int fq) const {
;     ...
;                 if (mode == EPI_SWIGLU) rs = frsq(rowsq[row] * (1.0f / DM) + 1e-6f);
;     ...
;                     } else {
;                         v0 = v0 * rs; v1 = v1 * rs;
;                         u32x2 w; w.x = pk2(fsilu(v0[0]) * v1[0], fsilu(v0[1]) * v1[1]); w.y = pk2(fsilu(v0[2]) * v1[2], fsilu(v0[3]) * v1[3]);
;                         *(u32x2*)(O + (size_t)row * ldc + (col >> 1)) = w;
;                     }
	v_fmamk_f32 v244, v238, 0x3a000000, v158
	v_rsq_f32_e32 v245, v244
	v_ashrrev_i32_e32 v97, 31, v96
	v_lshl_add_u64 v[102:103], v[96:97], 2, s[74:75]
	v_mul_f32_e32 v245, 0xbfb8aa3b, v245
	v_mul_f32_e32 v97, v245, v92
	v_mul_f32_e32 v100, v245, v93
	v_mul_f32_e32 v101, v245, v94
	v_mul_f32_e32 v104, v245, v95
	v_mul_f32_e32 v105, v245, v84
	v_mul_f32_e32 v106, v245, v85
	v_mul_f32_e32 v107, v245, v86
	v_mul_f32_e32 v108, v245, v87
	v_exp_f32_e32 v97, v97
	v_exp_f32_e32 v100, v100
	v_exp_f32_e32 v101, v101
	v_exp_f32_e32 v104, v104
	v_exp_f32_e32 v105, v105
	v_exp_f32_e32 v106, v106
	v_exp_f32_e32 v107, v107
	v_exp_f32_e32 v108, v108
	v_fma_f32 v97, v97, v244, v244
	v_fma_f32 v109, v100, v244, v244
	v_fma_f32 v110, v101, v244, v244
	v_fma_f32 v111, v104, v244, v244
	v_fma_f32 v112, v105, v244, v244
	v_fma_f32 v113, v106, v244, v244
	v_fma_f32 v114, v107, v244, v244
	v_fma_f32 v115, v108, v244, v244
	v_rcp_f32_e32 v100, v97
	v_rcp_f32_e32 v101, v109
	v_rcp_f32_e32 v104, v110
	v_rcp_f32_e32 v105, v111
	v_rcp_f32_e32 v106, v112
	v_rcp_f32_e32 v107, v113
	v_rcp_f32_e32 v108, v114
	v_rcp_f32_e32 v109, v115
	v_pk_mul_f32 v[92:93], v[92:93], v[100:101]
	v_pk_mul_f32 v[94:95], v[94:95], v[104:105]
	v_pk_mul_f32 v[84:85], v[84:85], v[106:107]
	v_pk_mul_f32 v[86:87], v[86:87], v[108:109]
	v_pk_mul_f32 v[88:89], v[88:89], v[92:93]
	v_pk_mul_f32 v[90:91], v[90:91], v[94:95]
	v_pk_mul_f32 v[80:81], v[80:81], v[84:85]
	v_pk_mul_f32 v[82:83], v[82:83], v[86:87]
	v_cvt_pk_bf16_f32 v84, v88, v89
	v_cvt_pk_bf16_f32 v85, v90, v91
	v_cvt_pk_bf16_f32 v80, v80, v81
	v_cvt_pk_bf16_f32 v81, v82, v83
	global_store_dwordx2 v[98:99], v[84:85], off
	global_store_dwordx2 v[98:99], v[80:81], off offset:128
	v_mad_i64_i32 v[82:83], s[24:25], v96, s39, v[146:147]
	v_lshl_add_u64 v[82:83], v[82:83], 0, v[150:151]
	s_waitcnt vmcnt(10)
	v_fmamk_f32 v244, v239, 0x3a000000, v158
	v_rsq_f32_e32 v245, v244
	s_nop 0
	v_mul_f32_e32 v245, 0xbfb8aa3b, v245
	v_mul_f32_e32 v80, v245, v76
	v_mul_f32_e32 v81, v245, v77
	v_mul_f32_e32 v84, v245, v78
	v_mul_f32_e32 v85, v245, v79
	v_mul_f32_e32 v86, v245, v68
	v_mul_f32_e32 v87, v245, v69
	v_mul_f32_e32 v88, v245, v70
	v_mul_f32_e32 v89, v245, v71
	v_exp_f32_e32 v80, v80
	v_exp_f32_e32 v81, v81
	v_exp_f32_e32 v84, v84
	v_exp_f32_e32 v85, v85
	v_exp_f32_e32 v86, v86
	v_exp_f32_e32 v87, v87
	v_exp_f32_e32 v88, v88
	v_exp_f32_e32 v89, v89
	v_fma_f32 v80, v80, v244, v244
	v_fma_f32 v81, v81, v244, v244
	v_fma_f32 v84, v84, v244, v244
	v_fma_f32 v85, v85, v244, v244
	v_fma_f32 v86, v86, v244, v244
	v_fma_f32 v87, v87, v244, v244
	v_fma_f32 v88, v88, v244, v244
	v_fma_f32 v89, v89, v244, v244
	v_rcp_f32_e32 v80, v80
	v_rcp_f32_e32 v81, v81
	v_rcp_f32_e32 v84, v84
	v_rcp_f32_e32 v85, v85
	v_rcp_f32_e32 v86, v86
	v_rcp_f32_e32 v87, v87
	v_rcp_f32_e32 v88, v88
	v_rcp_f32_e32 v89, v89
	v_pk_mul_f32 v[76:77], v[76:77], v[80:81]
	v_pk_mul_f32 v[78:79], v[78:79], v[84:85]
	v_pk_mul_f32 v[68:69], v[68:69], v[86:87]
	v_pk_mul_f32 v[70:71], v[70:71], v[88:89]
	v_pk_mul_f32 v[72:73], v[72:73], v[76:77]
	v_pk_mul_f32 v[74:75], v[74:75], v[78:79]
	v_pk_mul_f32 v[64:65], v[64:65], v[68:69]
	v_pk_mul_f32 v[66:67], v[66:67], v[70:71]
	v_cvt_pk_bf16_f32 v68, v72, v73
	v_cvt_pk_bf16_f32 v69, v74, v75
	v_cvt_pk_bf16_f32 v64, v64, v65
	v_cvt_pk_bf16_f32 v65, v66, v67
	global_store_dwordx2 v[82:83], v[68:69], off
	global_store_dwordx2 v[82:83], v[64:65], off offset:128
	v_add_u32_e32 v65, 0x80, v144
	v_mad_i64_i32 v[66:67], s[24:25], v65, s39, v[146:147]
	v_lshl_add_u64 v[66:67], v[66:67], 0, v[150:151]
	s_waitcnt vmcnt(11)
	v_fmamk_f32 v244, v240, 0x3a000000, v158
	v_rsq_f32_e32 v245, v244
	s_nop 0
	v_mul_f32_e32 v245, 0xbfb8aa3b, v245
	v_mul_f32_e32 v64, v245, v60
	v_mul_f32_e32 v65, v245, v61
	v_mul_f32_e32 v68, v245, v62
	v_mul_f32_e32 v69, v245, v63
	v_mul_f32_e32 v70, v245, v52
	v_mul_f32_e32 v71, v245, v53
	v_mul_f32_e32 v72, v245, v54
	v_mul_f32_e32 v73, v245, v55
	v_exp_f32_e32 v64, v64
	v_exp_f32_e32 v65, v65
	v_exp_f32_e32 v68, v68
	v_exp_f32_e32 v69, v69
	v_exp_f32_e32 v70, v70
	v_exp_f32_e32 v71, v71
	v_exp_f32_e32 v72, v72
	v_exp_f32_e32 v73, v73
	v_fma_f32 v64, v64, v244, v244
	v_fma_f32 v65, v65, v244, v244
	v_fma_f32 v68, v68, v244, v244
	v_fma_f32 v69, v69, v244, v244
	v_fma_f32 v70, v70, v244, v244
	v_fma_f32 v71, v71, v244, v244
	v_fma_f32 v72, v72, v244, v244
	v_fma_f32 v73, v73, v244, v244
	v_rcp_f32_e32 v64, v64
	v_rcp_f32_e32 v65, v65
	v_rcp_f32_e32 v68, v68
	v_rcp_f32_e32 v69, v69
	v_rcp_f32_e32 v70, v70
	v_rcp_f32_e32 v71, v71
	v_rcp_f32_e32 v72, v72
	v_rcp_f32_e32 v73, v73
	v_pk_mul_f32 v[60:61], v[60:61], v[64:65]
	v_pk_mul_f32 v[62:63], v[62:63], v[68:69]
	v_pk_mul_f32 v[52:53], v[52:53], v[70:71]
	v_pk_mul_f32 v[54:55], v[54:55], v[72:73]
	v_pk_mul_f32 v[56:57], v[56:57], v[60:61]
	v_pk_mul_f32 v[58:59], v[58:59], v[62:63]
	v_pk_mul_f32 v[48:49], v[48:49], v[52:53]
	v_pk_mul_f32 v[50:51], v[50:51], v[54:55]
	v_cvt_pk_bf16_f32 v52, v56, v57
	v_cvt_pk_bf16_f32 v53, v58, v59
	v_cvt_pk_bf16_f32 v48, v48, v49
	v_cvt_pk_bf16_f32 v49, v50, v51
	global_store_dwordx2 v[66:67], v[52:53], off
	global_store_dwordx2 v[66:67], v[48:49], off offset:128
	v_add_u32_e32 v49, 0x90, v144
	v_mad_i64_i32 v[50:51], s[24:25], v49, s39, v[146:147]
	v_lshl_add_u64 v[50:51], v[50:51], 0, v[150:151]
	s_waitcnt vmcnt(12)
; DI unsigned pk2(float lo, float hi) { const f32x2 v = {lo, hi}; const hwbf16x2 b = __builtin_convertvector(v, hwbf16x2); return __builtin_bit_cast(unsigned, b); }
; DI float fsilu(float v) { return v * frcp(1.f + __expf(-v)); }
; #define PG8_BAR __builtin_amdgcn_s_barrier()
;     DI void operator()(const f32x4 (&acc)[2][2][4][2], const Unit& u, int wr, int wc, int fr, int fq) const {
;     ...
;                     } else {
;                         v0 = v0 * rs; v1 = v1 * rs;
;                         u32x2 w; w.x = pk2(fsilu(v0[0]) * v1[0], fsilu(v0[1]) * v1[1]); w.y = pk2(fsilu(v0[2]) * v1[2], fsilu(v0[3]) * v1[3]);
;                         *(u32x2*)(O + (size_t)row * ldc + (col >> 1)) = w;
;                     }
; DI void gemm_phase(LAS unsigned char* lds, const Gemm g, const StaticOrder& S, const Epi& E) {
;     ...
;         if (!has_next) break;
; #pragma unroll
;         for (int a = 0; a < 2; ++a)
; #pragma unroll
;             for (int b = 0; b < 2; ++b)
; #pragma unroll
;                 for (int m = 0; m < 4; ++m)
; #pragma unroll
;                     for (int n = 0; n < 2; ++n) acc[a][b][m][n] = (f32x4){0.f, 0.f, 0.f, 0.f};
;         cur = nxt; cA = nA; cB = nB; ++ui;
;         if (wr == 1) PG8_BAR;
	v_fmamk_f32 v244, v241, 0x3a000000, v158
	v_rsq_f32_e32 v245, v244
	s_nop 0
	v_mul_f32_e32 v245, 0xbfb8aa3b, v245
	v_mul_f32_e32 v48, v245, v44
	v_mul_f32_e32 v49, v245, v45
	v_mul_f32_e32 v52, v245, v46
	v_mul_f32_e32 v53, v245, v47
	v_mul_f32_e32 v54, v245, v36
	v_mul_f32_e32 v55, v245, v37
	v_mul_f32_e32 v56, v245, v38
	v_mul_f32_e32 v57, v245, v39
	v_exp_f32_e32 v48, v48
	v_exp_f32_e32 v49, v49
	v_exp_f32_e32 v52, v52
	v_exp_f32_e32 v53, v53
	v_exp_f32_e32 v54, v54
	v_exp_f32_e32 v55, v55
	v_exp_f32_e32 v56, v56
	v_exp_f32_e32 v57, v57
	v_fma_f32 v48, v48, v244, v244
	v_fma_f32 v49, v49, v244, v244
	v_fma_f32 v52, v52, v244, v244
	v_fma_f32 v53, v53, v244, v244
	v_fma_f32 v54, v54, v244, v244
	v_fma_f32 v55, v55, v244, v244
	v_fma_f32 v56, v56, v244, v244
	v_fma_f32 v57, v57, v244, v244
	v_rcp_f32_e32 v48, v48
	v_rcp_f32_e32 v49, v49
	v_rcp_f32_e32 v52, v52
	v_rcp_f32_e32 v53, v53
	v_rcp_f32_e32 v54, v54
	v_rcp_f32_e32 v55, v55
	v_rcp_f32_e32 v56, v56
	v_rcp_f32_e32 v57, v57
	v_pk_mul_f32 v[44:45], v[44:45], v[48:49]
	v_pk_mul_f32 v[46:47], v[46:47], v[52:53]
	v_pk_mul_f32 v[36:37], v[36:37], v[54:55]
	v_pk_mul_f32 v[38:39], v[38:39], v[56:57]
	v_pk_mul_f32 v[40:41], v[40:41], v[44:45]
	v_pk_mul_f32 v[42:43], v[42:43], v[46:47]
	v_pk_mul_f32 v[32:33], v[32:33], v[36:37]
	v_pk_mul_f32 v[34:35], v[34:35], v[38:39]
	v_cvt_pk_bf16_f32 v36, v40, v41
	v_cvt_pk_bf16_f32 v37, v42, v43
	v_cvt_pk_bf16_f32 v32, v32, v33
	v_cvt_pk_bf16_f32 v33, v34, v35
	global_store_dwordx2 v[50:51], v[36:37], off
	global_store_dwordx2 v[50:51], v[32:33], off offset:128
	v_add_u32_e32 v33, 0xa0, v144
	v_mad_i64_i32 v[34:35], s[24:25], v33, s39, v[146:147]
	v_lshl_add_u64 v[34:35], v[34:35], 0, v[150:151]
	s_waitcnt vmcnt(13)
	v_fmamk_f32 v244, v242, 0x3a000000, v158
	v_rsq_f32_e32 v245, v244
	s_nop 0
	v_mul_f32_e32 v245, 0xbfb8aa3b, v245
	v_mul_f32_e32 v32, v245, v28
	v_mul_f32_e32 v33, v245, v29
	v_mul_f32_e32 v36, v245, v30
	v_mul_f32_e32 v37, v245, v31
	v_mul_f32_e32 v38, v245, v20
	v_mul_f32_e32 v39, v245, v21
	v_mul_f32_e32 v40, v245, v22
	v_mul_f32_e32 v41, v245, v23
	v_exp_f32_e32 v32, v32
	v_exp_f32_e32 v33, v33
	v_exp_f32_e32 v36, v36
	v_exp_f32_e32 v37, v37
	v_exp_f32_e32 v38, v38
	v_exp_f32_e32 v39, v39
	v_exp_f32_e32 v40, v40
	v_exp_f32_e32 v41, v41
	v_fma_f32 v32, v32, v244, v244
	v_fma_f32 v33, v33, v244, v244
	v_fma_f32 v36, v36, v244, v244
	v_fma_f32 v37, v37, v244, v244
	v_fma_f32 v38, v38, v244, v244
	v_fma_f32 v39, v39, v244, v244
	v_fma_f32 v40, v40, v244, v244
	v_fma_f32 v41, v41, v244, v244
	v_rcp_f32_e32 v32, v32
	v_rcp_f32_e32 v33, v33
	v_rcp_f32_e32 v36, v36
	v_rcp_f32_e32 v37, v37
	v_rcp_f32_e32 v38, v38
	v_rcp_f32_e32 v39, v39
	v_rcp_f32_e32 v40, v40
	v_rcp_f32_e32 v41, v41
	v_pk_mul_f32 v[28:29], v[28:29], v[32:33]
	v_pk_mul_f32 v[30:31], v[30:31], v[36:37]
	v_pk_mul_f32 v[20:21], v[20:21], v[38:39]
	v_pk_mul_f32 v[22:23], v[22:23], v[40:41]
	v_pk_mul_f32 v[24:25], v[24:25], v[28:29]
	v_pk_mul_f32 v[26:27], v[26:27], v[30:31]
	v_pk_mul_f32 v[16:17], v[16:17], v[20:21]
	v_pk_mul_f32 v[18:19], v[18:19], v[22:23]
	v_cvt_pk_bf16_f32 v20, v24, v25
	v_cvt_pk_bf16_f32 v21, v26, v27
	v_cvt_pk_bf16_f32 v16, v16, v17
	v_cvt_pk_bf16_f32 v17, v18, v19
	global_store_dwordx2 v[34:35], v[20:21], off
	global_store_dwordx2 v[34:35], v[16:17], off offset:128
	v_add_u32_e32 v17, 0xb0, v144
	v_mad_i64_i32 v[18:19], s[24:25], v17, s39, v[146:147]
	v_lshl_add_u64 v[18:19], v[18:19], 0, v[150:151]
	s_waitcnt vmcnt(14)
	v_fmamk_f32 v244, v243, 0x3a000000, v158
	v_rsq_f32_e32 v245, v244
	s_nop 0
	v_mul_f32_e32 v245, 0xbfb8aa3b, v245
	v_mul_f32_e32 v16, v245, v12
	v_mul_f32_e32 v17, v245, v13
	v_mul_f32_e32 v20, v245, v14
	v_mul_f32_e32 v21, v245, v15
	v_mul_f32_e32 v22, v245, v4
	v_mul_f32_e32 v23, v245, v5
	v_mul_f32_e32 v24, v245, v6
	v_mul_f32_e32 v25, v245, v7
	v_exp_f32_e32 v16, v16
	v_exp_f32_e32 v17, v17
	v_exp_f32_e32 v20, v20
	v_exp_f32_e32 v21, v21
	v_exp_f32_e32 v22, v22
	v_exp_f32_e32 v23, v23
	v_exp_f32_e32 v24, v24
	v_exp_f32_e32 v25, v25
	v_fma_f32 v16, v16, v244, v244
	v_fma_f32 v17, v17, v244, v244
	v_fma_f32 v20, v20, v244, v244
	v_fma_f32 v21, v21, v244, v244
	v_fma_f32 v22, v22, v244, v244
	v_fma_f32 v23, v23, v244, v244
	v_fma_f32 v24, v24, v244, v244
	v_fma_f32 v25, v25, v244, v244
	v_rcp_f32_e32 v16, v16
	v_rcp_f32_e32 v17, v17
	v_rcp_f32_e32 v20, v20
	v_rcp_f32_e32 v21, v21
	v_rcp_f32_e32 v22, v22
	v_rcp_f32_e32 v23, v23
	v_rcp_f32_e32 v24, v24
	v_rcp_f32_e32 v25, v25
	v_pk_mul_f32 v[12:13], v[12:13], v[16:17]
	v_pk_mul_f32 v[14:15], v[14:15], v[20:21]
	v_pk_mul_f32 v[4:5], v[4:5], v[22:23]
	v_pk_mul_f32 v[6:7], v[6:7], v[24:25]
	v_pk_mul_f32 v[8:9], v[8:9], v[12:13]
	v_pk_mul_f32 v[10:11], v[10:11], v[14:15]
	v_pk_mul_f32 v[0:1], v[0:1], v[4:5]
	v_pk_mul_f32 v[2:3], v[2:3], v[6:7]
	v_cvt_pk_bf16_f32 v4, v8, v9
	v_cvt_pk_bf16_f32 v5, v10, v11
	v_cvt_pk_bf16_f32 v0, v0, v1
	v_cvt_pk_bf16_f32 v1, v2, v3
	global_store_dwordx2 v[18:19], v[4:5], off
	global_store_dwordx2 v[18:19], v[0:1], off offset:128
	s_cbranch_vccnz .LBB0_1016
	s_andn2_b64 vcc, exec, s[6:7]
	s_cbranch_vccnz .LBB0_1015
	s_barrier
	s_branch .LBB0_1015
